# layer-1 weight transposes moved from prologue into idle WGs of layer-0 P5 tail round
# speedup vs baseline: 1.0293x; 1.0045x over previous
; DEVI const float* IN(int i) { return *(const float* const __attribute__((address_space(4)))*)(kargs() + 8 * i); }
; DEVI void prologue(int wv, LAS unsigned char* lds) {
;     ...
;     for (int it = gw; it < 2 * I_L; it += NGW) {
;         const int l = it / I_L; int r = it % I_L;
;         unsigned char* wl = ws + O_W + (size_t)l * W_LAYER;
;         if (r < I_IN) { const int kb = r / 101, nb = r % 101, n0 = nb * 32;
;             const int d0 = n0 < 384 ? n0 : n0 < 640 ? 512 + (n0 - 384) : n0 < 672 ? 384 + (n0 - 640) : n0 < 1184 ? 768 + (n0 - 672) : n0 < 2208 ? 1280 + (n0 - 1184) : 2304 + (n0 - 2208);
;             tr_item(IN(6) + (size_t)l * 1024 * 3232, 3232, 1024, IN(5) + l * 1024, (bf16_t*)(wl + W_IN), d0, scr, kb * 64, n0, lane); continue; }
.LBB0_23:
	s_or_b64 exec, exec, s[2:3]
	s_mov_b32 s16, s85
	s_mov_b32 s18, s95
	s_mov_b64 s[6:7], s[0:1]
	s_waitcnt lgkmcnt(0)
	s_barrier
	v_mbcnt_lo_u32_b32 v64, -1, 0
	v_mbcnt_hi_u32_b32 v64, -1, v64
	v_lshl_or_b32 v64, s33, 6, v64
	s_load_dwordx2 s[20:21], s[6:7], 0xb0
	v_readfirstlane_b32 s2, v64
	s_ashr_i32 s2, s2, 6
	s_lshl_b32 s3, s18, 3
	v_and_b32_e32 v34, 63, v64
	s_add_i32 s4, s3, s2
	s_lshl_b32 s14, s16, 3
	s_ashr_i32 s17, s16, 31
	v_ashrrev_i32_e32 v65, 31, v64
	s_movk_i32 s52, 0x35bf
	s_cmp_eq_u32 s16, 0x100
	s_cselect_b32 s52, 0x1adf, s52
	s_cmp_gt_i32 s4, s52
	v_lshlrev_b32_e32 v66, 3, v34
	s_cbranch_scc1 .LBB0_328
	v_lshrrev_b32_e32 v0, 5, v34
	s_movk_i32 s3, 0x84
	v_mov_b32_e32 v1, 0x108
	v_mad_u32_u24 v13, v0, s3, v1
	v_mov_b32_e32 v1, 0x210
	v_mad_u32_u24 v15, v0, s3, v1
	v_mov_b32_e32 v1, 0x318
	v_mad_u32_u24 v17, v0, s3, v1
	v_mov_b32_e32 v1, 0x420
	v_mad_u32_u24 v19, v0, s3, v1
	v_mov_b32_e32 v1, 0x528
	v_mad_u32_u24 v21, v0, s3, v1
	v_mov_b32_e32 v1, 0x630
	v_mad_u32_u24 v23, v0, s3, v1
	v_mov_b32_e32 v1, 0x738
	v_mad_u32_u24 v25, v0, s3, v1
	v_mov_b32_e32 v1, 0x840
	v_mad_u32_u24 v27, v0, s3, v1
	v_mov_b32_e32 v1, 0x948
	v_mad_u32_u24 v29, v0, s3, v1
	v_mov_b32_e32 v1, 0xa50
	v_mad_u32_u24 v31, v0, s3, v1
	v_mov_b32_e32 v1, 0xb58
	v_mad_u32_u24 v33, v0, s3, v1
	v_mov_b32_e32 v1, 0xc60
	v_mad_u32_u24 v36, v0, s3, v1
	v_mov_b32_e32 v1, 0xd68
	v_mad_u32_u24 v38, v0, s3, v1
	v_mov_b32_e32 v1, 0xe70
	v_mad_u32_u24 v40, v0, s3, v1
	v_mov_b32_e32 v1, 0xf78
	v_mad_u32_u24 v42, v0, s3, v1
	v_mov_b32_e32 v1, 0x1080
	v_mad_u32_u24 v44, v0, s3, v1
	v_mov_b32_e32 v1, 0x1188
	v_mad_u32_u24 v46, v0, s3, v1
	v_mov_b32_e32 v1, 0x1290
	v_mad_u32_u24 v48, v0, s3, v1
	v_mov_b32_e32 v1, 0x1398
	v_mad_u32_u24 v50, v0, s3, v1
	v_mov_b32_e32 v1, 0x14a0
	v_mad_u32_u24 v51, v0, s3, v1
	v_mov_b32_e32 v1, 0x15a8
	v_mad_u32_u24 v52, v0, s3, v1
	v_mov_b32_e32 v1, 0x16b0
	s_mulk_i32 s2, 0x2100
	v_mad_u32_u24 v53, v0, s3, v1
	v_mov_b32_e32 v1, 0x17b8
	v_lshrrev_b32_e32 v55, 3, v34
	v_and_b32_e32 v6, 56, v66
	s_add_i32 s2, s2, 0
	v_mad_u32_u24 v54, v0, s3, v1
	v_mul_u32_u24_e32 v1, 0x84, v6
	v_lshlrev_b32_e32 v4, 2, v55
	s_waitcnt lgkmcnt(0)
	s_add_u32 s5, s20, 0x390800
	v_and_b32_e32 v2, 31, v64
	v_mov_b32_e32 v5, 0
	v_add3_u32 v56, s2, v1, v4
	v_mov_b32_e32 v1, 0x18c0
	s_mov_b32 s7, 0
	s_addc_u32 s15, s21, 0
	v_lshl_add_u32 v3, v2, 2, s2
	v_mul_u32_u24_e32 v7, 0x84, v0
	v_or_b32_e32 v12, 2, v0
	v_or_b32_e32 v14, 4, v0
	v_or_b32_e32 v16, 6, v0
	v_or_b32_e32 v18, 8, v0
	v_or_b32_e32 v20, 10, v0
	v_or_b32_e32 v22, 12, v0
	v_or_b32_e32 v24, 14, v0
	v_or_b32_e32 v26, 16, v0
	v_or_b32_e32 v28, 18, v0
	v_or_b32_e32 v30, 20, v0
	v_or_b32_e32 v32, 22, v0
	v_or_b32_e32 v35, 24, v0
	v_or_b32_e32 v37, 26, v0
	v_or_b32_e32 v39, 28, v0
	v_or_b32_e32 v41, 30, v0
	v_or_b32_e32 v43, 32, v0
	v_or_b32_e32 v45, 34, v0
	v_or_b32_e32 v47, 36, v0
	v_or_b32_e32 v49, 38, v0
	v_mad_u32_u24 v57, v0, s3, v1
	v_mov_b32_e32 v1, v5
	s_lshl_b32 s19, s4, 1
	s_lshl_b32 s40, s16, 4
	s_lshl_b32 s41, s4, 5
	s_lshl_b32 s42, s16, 8
	s_mov_b64 s[8:9], 0x1410000
	s_mov_b64 s[10:11], 0xc10000
	s_mov_b64 s[12:13], 0xa10000
	s_mov_b64 s[22:23], 0x810000
	s_movk_i32 s43, 0xf920
	s_movk_i32 s44, 0x300
	s_movk_i32 s45, 0xc00
	s_mov_b64 s[24:25], 0x680000
	s_mov_b32 s46, s4
	v_or_b32_e32 v58, 40, v0
	v_or_b32_e32 v59, 42, v0
	v_or_b32_e32 v60, 44, v0
	v_or_b32_e32 v61, 46, v0
	v_or_b32_e32 v62, 48, v0
	v_or_b32_e32 v63, 50, v0
	v_or_b32_e32 v67, 52, v0
	v_or_b32_e32 v68, 54, v0
	v_or_b32_e32 v69, 56, v0
	v_or_b32_e32 v70, 58, v0
	v_or_b32_e32 v71, 60, v0
	v_or_b32_e32 v72, 62, v0
	v_or_b32_e32 v73, 8, v55
	v_or_b32_e32 v74, 16, v55
	v_or_b32_e32 v75, 24, v55
	s_branch .LBB0_28

; DEVI const float* IN(int i) { return *(const float* const __attribute__((address_space(4)))*)(kargs() + 8 * i); }
; DEVI void prologue(int wv, LAS unsigned char* lds) {
;     ...
;     for (int it = gw; it < 2 * I_L; it += NGW) {
;         const int l = it / I_L; int r = it % I_L;
;         unsigned char* wl = ws + O_W + (size_t)l * W_LAYER;
;         if (r < I_IN) { const int kb = r / 101, nb = r % 101, n0 = nb * 32;
;             const int d0 = n0 < 384 ? n0 : n0 < 640 ? 512 + (n0 - 384) : n0 < 672 ? 384 + (n0 - 640) : n0 < 1184 ? 768 + (n0 - 672) : n0 < 2208 ? 1280 + (n0 - 1184) : 2304 + (n0 - 2208);
;             tr_item(IN(6) + (size_t)l * 1024 * 3232, 3232, 1024, IN(5) + l * 1024, (bf16_t*)(wl + W_IN), d0, scr, kb * 64, n0, lane); continue; }
.LBB0_27:
	s_add_i32 s46, s46, s14
	s_add_i32 s19, s19, s40
	s_add_i32 s41, s41, s42
	s_cmp_gt_i32 s46, s52
	s_cbranch_scc1 .LBB0_328

; DEVI const float* IN(int i) { return *(const float* const __attribute__((address_space(4)))*)(kargs() + 8 * i); }
; DEVI void prologue(int wv, LAS unsigned char* lds) {
;     ...
;     for (int it = gw; it < 2 * I_L; it += NGW) {
;         const int l = it / I_L; int r = it % I_L;
;         unsigned char* wl = ws + O_W + (size_t)l * W_LAYER;
;         if (r < I_IN) { const int kb = r / 101, nb = r % 101, n0 = nb * 32;
;             const int d0 = n0 < 384 ? n0 : n0 < 640 ? 512 + (n0 - 384) : n0 < 672 ? 384 + (n0 - 640) : n0 < 1184 ? 768 + (n0 - 672) : n0 < 2208 ? 1280 + (n0 - 1184) : 2304 + (n0 - 2208);
;             tr_item(IN(6) + (size_t)l * 1024 * 3232, 3232, 1024, IN(5) + l * 1024, (bf16_t*)(wl + W_IN), d0, scr, kb * 64, n0, lane); continue; }
;         r -= I_IN;
;         if (r < I_UQ) { const int kb = r / 24, nb = r % 24, n0 = nb * 32, hd = n0 / 96, dim0 = n0 % 96;
;             const int d0 = dim0 < 64 ? 256 * (hd >> 2) + 128 * (dim0 >> 5) + 32 * (hd & 3) : 512 + 128 * (hd >> 2) + 32 * (hd & 3);
;             tr_item(IN(9) + (size_t)l * 384 * 768, 768, 384, IN(7) + l * 384, (bf16_t*)(wl + W_UQ), d0, scr, kb * 64, n0, lane); continue; }
;         r -= I_UQ;
;         if (r < 2 * I_KV) { const int fold = r < I_KV; if (!fold) r -= I_KV;
;             const int kb = r / 32, nb = r % 32, n0 = nb * 32, hd = n0 / 128, dim0 = n0 % 128;
;             const bool isk = dim0 < 64;
;             const int d0 = isk ? 256 * (hd >> 2) + 128 * (dim0 >> 5) + 32 * (hd & 3) : hd * 64 + (dim0 - 64);
;             bf16_t* dst = (bf16_t*)(wl + (fold ? (isk ? W_K : W_V) : (isk ? W_KC : W_VC)));
;             tr_item(IN(10) + (size_t)l * 256 * 1024, 1024, 256, fold ? IN(8) + l * 256 : nullptr, dst, d0, scr, kb * 64, n0, lane); continue; }
;         r -= 2 * I_KV;
;         if (r < I_A) { tr_item(IN(13) + (size_t)l * 512 * 1024, 1024, 512, nullptr, (bf16_t*)(wl + W_A), (r % 32) * 32, scr, (r / 32) * 64, (r % 32) * 32, lane); continue; }
;         r -= I_A;
;         if (r < I_O) { tr_item(IN(17) + (size_t)l * 1024 * 1024, 1024, 1024, nullptr, (bf16_t*)(wl + W_O), (r % 32) * 32, scr, (r / 32) * 64, (r % 32) * 32, lane); continue; }
;         r -= I_O;
;         if (r < I_UP) { tr_item(IN(19) + (size_t)l * 1024 * 4096, 4096, 1024, IN(18) + l * 1024, (bf16_t*)(wl + W_UP), (r % 128) * 32, scr, (r / 128) * 64, (r % 128) * 32, lane); continue; }
;         r -= I_UP;
.LBB0_1559:
	s_waitcnt vmcnt(0) lgkmcnt(0)
	v_readlane_b32 vcc_lo, v255, 0
	v_readlane_b32 vcc_hi, v255, 5
	s_cmp_eq_u32 vcc_lo, 0
	s_cbranch_scc1 .Lsj5_skip
	s_load_dword vcc_lo, s[0:1], 0xb8
	s_waitcnt lgkmcnt(0)
	s_cmp_lg_u32 vcc_lo, 0x100
	s_cbranch_scc1 .Lsj5_skip
	s_sub_i32 vcc_hi, vcc_hi, 56
	s_and_b32 vcc_hi, vcc_hi, 0xff
	s_cmp_ge_u32 vcc_hi, 248
	s_cbranch_scc1 .Lsj5_skip
	v_writelane_b32 v201, s0, 0
	v_writelane_b32 v201, s1, 1
	v_writelane_b32 v201, s2, 2
	v_writelane_b32 v201, s3, 3
	v_writelane_b32 v201, s4, 4
	v_writelane_b32 v201, s5, 5
	v_writelane_b32 v201, s6, 6
	v_writelane_b32 v201, s7, 7
	v_writelane_b32 v201, s8, 8
	v_writelane_b32 v201, s9, 9
	v_writelane_b32 v201, s10, 10
	v_writelane_b32 v201, s11, 11
	v_writelane_b32 v201, s12, 12
	v_writelane_b32 v201, s13, 13
	v_writelane_b32 v201, s14, 14
	v_writelane_b32 v201, s15, 15
	v_writelane_b32 v201, s16, 16
	v_writelane_b32 v201, s17, 17
	v_writelane_b32 v201, s18, 18
	v_writelane_b32 v201, s19, 19
	v_writelane_b32 v201, s20, 20
	v_writelane_b32 v201, s21, 21
	v_writelane_b32 v201, s22, 22
	v_writelane_b32 v201, s23, 23
	v_writelane_b32 v201, s24, 24
	v_writelane_b32 v201, s25, 25
	v_writelane_b32 v201, s26, 26
	v_writelane_b32 v201, s27, 27
	v_writelane_b32 v201, s28, 28
	v_writelane_b32 v201, s29, 29
	v_writelane_b32 v201, s30, 30
	v_writelane_b32 v201, s31, 31
	v_writelane_b32 v201, s32, 32
	v_writelane_b32 v201, s33, 33
	v_writelane_b32 v201, s34, 34
	v_writelane_b32 v201, s35, 35
	v_writelane_b32 v201, s36, 36
	v_writelane_b32 v201, s37, 37
	v_writelane_b32 v201, s38, 38
	v_writelane_b32 v201, s39, 39
	v_writelane_b32 v201, s40, 40
	v_writelane_b32 v201, s41, 41
	v_writelane_b32 v201, s42, 42
	v_writelane_b32 v201, s43, 43
	v_writelane_b32 v201, s44, 44
	v_writelane_b32 v201, s45, 45
	v_writelane_b32 v201, s46, 46
	v_writelane_b32 v201, s47, 47
	v_writelane_b32 v201, s48, 48
	v_writelane_b32 v201, s49, 49
	v_writelane_b32 v201, s50, 50
	v_writelane_b32 v201, s51, 51
	v_writelane_b32 v201, s52, 52
	v_writelane_b32 v201, s53, 53
	v_writelane_b32 v201, s54, 54
	v_writelane_b32 v201, s55, 55
	v_writelane_b32 v201, s56, 56
	v_writelane_b32 v201, s57, 57
	v_writelane_b32 v201, s58, 58
	v_writelane_b32 v201, s59, 59
	v_writelane_b32 v201, s60, 60
	v_writelane_b32 v201, s61, 61
	v_writelane_b32 v201, s62, 62
	v_writelane_b32 v201, s63, 63
	v_writelane_b32 v202, s64, 0
	v_writelane_b32 v202, s65, 1
	v_writelane_b32 v202, s66, 2
	v_writelane_b32 v202, s67, 3
	v_writelane_b32 v202, s68, 4
	v_writelane_b32 v202, s69, 5
	v_writelane_b32 v202, s70, 6
	v_writelane_b32 v202, s71, 7
	v_writelane_b32 v202, s72, 8
	v_writelane_b32 v202, s73, 9
	v_writelane_b32 v202, s74, 10
	v_writelane_b32 v202, s75, 11
	v_writelane_b32 v202, s76, 12
	v_writelane_b32 v202, s77, 13
	v_writelane_b32 v202, s78, 14
	v_writelane_b32 v202, s79, 15
	v_writelane_b32 v202, s80, 16
	v_writelane_b32 v202, s81, 17
	v_writelane_b32 v202, s82, 18
	v_writelane_b32 v202, s83, 19
	v_writelane_b32 v202, s84, 20
	v_writelane_b32 v202, s85, 21
	v_writelane_b32 v202, s86, 22
	v_writelane_b32 v202, s87, 23
	v_writelane_b32 v202, s88, 24
	v_writelane_b32 v202, s89, 25
	v_writelane_b32 v202, s90, 26
	v_writelane_b32 v202, s91, 27
	v_writelane_b32 v202, s92, 28
	v_writelane_b32 v202, s93, 29
	v_writelane_b32 v202, s94, 30
	v_writelane_b32 v202, s95, 31
	v_writelane_b32 v202, s96, 32
	v_writelane_b32 v202, s97, 33
	v_writelane_b32 v202, s98, 34
	v_writelane_b32 v202, s99, 35
	v_mov_b32_e32 v200, v1
	s_mov_b32 s16, 248
	s_mov_b32 s18, vcc_hi
	s_mov_b64 s[6:7], s[0:1]
	v_mbcnt_lo_u32_b32 v64, -1, 0
	v_mbcnt_hi_u32_b32 v64, -1, v64
	v_lshl_or_b32 v64, s33, 6, v64
	s_load_dwordx2 s[20:21], s[6:7], 0xb0
	v_readfirstlane_b32 s2, v64
	s_ashr_i32 s2, s2, 6
	s_lshl_b32 s3, s18, 3
	v_and_b32_e32 v34, 63, v64
	s_add_i32 s4, s3, s2
	s_addk_i32 s4, 0x1ae0
	s_lshl_b32 s14, s16, 3
	s_ashr_i32 s17, s16, 31
	v_ashrrev_i32_e32 v65, 31, v64
	s_cmpk_gt_i32 s4, 0x35bf
	v_lshlrev_b32_e32 v66, 3, v34
	s_cbranch_scc1 .Lsj5_end
	v_lshrrev_b32_e32 v0, 5, v34
	s_movk_i32 s3, 0x84
	v_mov_b32_e32 v1, 0x108
	v_mad_u32_u24 v13, v0, s3, v1
	v_mov_b32_e32 v1, 0x210
	v_mad_u32_u24 v15, v0, s3, v1
	v_mov_b32_e32 v1, 0x318
	v_mad_u32_u24 v17, v0, s3, v1
	v_mov_b32_e32 v1, 0x420
	v_mad_u32_u24 v19, v0, s3, v1
	v_mov_b32_e32 v1, 0x528
	v_mad_u32_u24 v21, v0, s3, v1
	v_mov_b32_e32 v1, 0x630
	v_mad_u32_u24 v23, v0, s3, v1
	v_mov_b32_e32 v1, 0x738
	v_mad_u32_u24 v25, v0, s3, v1
	v_mov_b32_e32 v1, 0x840
	v_mad_u32_u24 v27, v0, s3, v1
	v_mov_b32_e32 v1, 0x948
	v_mad_u32_u24 v29, v0, s3, v1
	v_mov_b32_e32 v1, 0xa50
	v_mad_u32_u24 v31, v0, s3, v1
	v_mov_b32_e32 v1, 0xb58
	v_mad_u32_u24 v33, v0, s3, v1
	v_mov_b32_e32 v1, 0xc60
	v_mad_u32_u24 v36, v0, s3, v1
	v_mov_b32_e32 v1, 0xd68
	v_mad_u32_u24 v38, v0, s3, v1
	v_mov_b32_e32 v1, 0xe70
	v_mad_u32_u24 v40, v0, s3, v1
	v_mov_b32_e32 v1, 0xf78
	v_mad_u32_u24 v42, v0, s3, v1
	v_mov_b32_e32 v1, 0x1080
	v_mad_u32_u24 v44, v0, s3, v1
	v_mov_b32_e32 v1, 0x1188
	v_mad_u32_u24 v46, v0, s3, v1
	v_mov_b32_e32 v1, 0x1290
	v_mad_u32_u24 v48, v0, s3, v1
	v_mov_b32_e32 v1, 0x1398
	v_mad_u32_u24 v50, v0, s3, v1
	v_mov_b32_e32 v1, 0x14a0
	v_mad_u32_u24 v51, v0, s3, v1
	v_mov_b32_e32 v1, 0x15a8
	v_mad_u32_u24 v52, v0, s3, v1
	v_mov_b32_e32 v1, 0x16b0
	s_mulk_i32 s2, 0x2100
	v_mad_u32_u24 v53, v0, s3, v1
	v_mov_b32_e32 v1, 0x17b8
	v_lshrrev_b32_e32 v55, 3, v34
	v_and_b32_e32 v6, 56, v66
	s_add_i32 s2, s2, 0
	v_mad_u32_u24 v54, v0, s3, v1
	v_mul_u32_u24_e32 v1, 0x84, v6
	v_lshlrev_b32_e32 v4, 2, v55
	s_waitcnt lgkmcnt(0)
	s_add_u32 s5, s20, 0x390800
	v_and_b32_e32 v2, 31, v64
	v_mov_b32_e32 v5, 0
	v_add3_u32 v56, s2, v1, v4
	v_mov_b32_e32 v1, 0x18c0
	s_mov_b32 s7, 0
	s_addc_u32 s15, s21, 0
	v_lshl_add_u32 v3, v2, 2, s2
	v_mul_u32_u24_e32 v7, 0x84, v0
	v_or_b32_e32 v12, 2, v0
	v_or_b32_e32 v14, 4, v0
	v_or_b32_e32 v16, 6, v0
	v_or_b32_e32 v18, 8, v0
	v_or_b32_e32 v20, 10, v0
	v_or_b32_e32 v22, 12, v0
	v_or_b32_e32 v24, 14, v0
	v_or_b32_e32 v26, 16, v0
	v_or_b32_e32 v28, 18, v0
	v_or_b32_e32 v30, 20, v0
	v_or_b32_e32 v32, 22, v0
	v_or_b32_e32 v35, 24, v0
	v_or_b32_e32 v37, 26, v0
	v_or_b32_e32 v39, 28, v0
	v_or_b32_e32 v41, 30, v0
	v_or_b32_e32 v43, 32, v0
	v_or_b32_e32 v45, 34, v0
	v_or_b32_e32 v47, 36, v0
	v_or_b32_e32 v49, 38, v0
	v_mad_u32_u24 v57, v0, s3, v1
	v_mov_b32_e32 v1, v5
	s_lshl_b32 s19, s4, 1
	s_lshl_b32 s40, s16, 4
	s_lshl_b32 s41, s4, 5
	s_lshl_b32 s42, s16, 8
	s_mov_b64 s[8:9], 0x1410000
	s_mov_b64 s[10:11], 0xc10000
	s_mov_b64 s[12:13], 0xa10000
	s_mov_b64 s[22:23], 0x810000
	s_movk_i32 s43, 0xf920
	s_movk_i32 s44, 0x300
	s_movk_i32 s45, 0xc00
	s_mov_b64 s[24:25], 0x680000
	s_mov_b32 s46, s4
	v_or_b32_e32 v58, 40, v0
	v_or_b32_e32 v59, 42, v0
	v_or_b32_e32 v60, 44, v0
	v_or_b32_e32 v61, 46, v0
	v_or_b32_e32 v62, 48, v0
	v_or_b32_e32 v63, 50, v0
	v_or_b32_e32 v67, 52, v0
	v_or_b32_e32 v68, 54, v0
	v_or_b32_e32 v69, 56, v0
	v_or_b32_e32 v70, 58, v0
	v_or_b32_e32 v71, 60, v0
	v_or_b32_e32 v72, 62, v0
	v_or_b32_e32 v73, 8, v55
	v_or_b32_e32 v74, 16, v55
	v_or_b32_e32 v75, 24, v55
	s_branch .Lsj5_28

; DEVI const float* IN(int i) { return *(const float* const __attribute__((address_space(4)))*)(kargs() + 8 * i); }
; DEVI void prologue(int wv, LAS unsigned char* lds) {
;     ...
;     for (int it = gw; it < 2 * I_L; it += NGW) {
;         const int l = it / I_L; int r = it % I_L;
;         unsigned char* wl = ws + O_W + (size_t)l * W_LAYER;
;         if (r < I_IN) { const int kb = r / 101, nb = r % 101, n0 = nb * 32;
;             const int d0 = n0 < 384 ? n0 : n0 < 640 ? 512 + (n0 - 384) : n0 < 672 ? 384 + (n0 - 640) : n0 < 1184 ? 768 + (n0 - 672) : n0 < 2208 ? 1280 + (n0 - 1184) : 2304 + (n0 - 2208);
;             tr_item(IN(6) + (size_t)l * 1024 * 3232, 3232, 1024, IN(5) + l * 1024, (bf16_t*)(wl + W_IN), d0, scr, kb * 64, n0, lane); continue; }
;         r -= I_IN;
;         if (r < I_UQ) { const int kb = r / 24, nb = r % 24, n0 = nb * 32, hd = n0 / 96, dim0 = n0 % 96;
;             const int d0 = dim0 < 64 ? 256 * (hd >> 2) + 128 * (dim0 >> 5) + 32 * (hd & 3) : 512 + 128 * (hd >> 2) + 32 * (hd & 3);
;             tr_item(IN(9) + (size_t)l * 384 * 768, 768, 384, IN(7) + l * 384, (bf16_t*)(wl + W_UQ), d0, scr, kb * 64, n0, lane); continue; }
;         r -= I_UQ;
;         if (r < 2 * I_KV) { const int fold = r < I_KV; if (!fold) r -= I_KV;
;             const int kb = r / 32, nb = r % 32, n0 = nb * 32, hd = n0 / 128, dim0 = n0 % 128;
;             const bool isk = dim0 < 64;
;             const int d0 = isk ? 256 * (hd >> 2) + 128 * (dim0 >> 5) + 32 * (hd & 3) : hd * 64 + (dim0 - 64);
;             bf16_t* dst = (bf16_t*)(wl + (fold ? (isk ? W_K : W_V) : (isk ? W_KC : W_VC)));
;             tr_item(IN(10) + (size_t)l * 256 * 1024, 1024, 256, fold ? IN(8) + l * 256 : nullptr, dst, d0, scr, kb * 64, n0, lane); continue; }
;         r -= 2 * I_KV;
;         if (r < I_A) { tr_item(IN(13) + (size_t)l * 512 * 1024, 1024, 512, nullptr, (bf16_t*)(wl + W_A), (r % 32) * 32, scr, (r / 32) * 64, (r % 32) * 32, lane); continue; }
;         r -= I_A;
;         if (r < I_O) { tr_item(IN(17) + (size_t)l * 1024 * 1024, 1024, 1024, nullptr, (bf16_t*)(wl + W_O), (r % 32) * 32, scr, (r / 32) * 64, (r % 32) * 32, lane); continue; }
;         r -= I_O;
;         if (r < I_UP) { tr_item(IN(19) + (size_t)l * 1024 * 4096, 4096, 1024, IN(18) + l * 1024, (bf16_t*)(wl + W_UP), (r % 128) * 32, scr, (r / 128) * 64, (r % 128) * 32, lane); continue; }
;         r -= I_UP;
.Lsj5_end:
	s_mov_b64 exec, -1
	s_waitcnt lgkmcnt(0)
	v_mov_b32_e32 v1, v200
	v_readlane_b32 s0, v201, 0
	v_readlane_b32 s1, v201, 1
	v_readlane_b32 s2, v201, 2
	v_readlane_b32 s3, v201, 3
	v_readlane_b32 s4, v201, 4
	v_readlane_b32 s5, v201, 5
	v_readlane_b32 s6, v201, 6
	v_readlane_b32 s7, v201, 7
	v_readlane_b32 s8, v201, 8
	v_readlane_b32 s9, v201, 9
	v_readlane_b32 s10, v201, 10
	v_readlane_b32 s11, v201, 11
	v_readlane_b32 s12, v201, 12
	v_readlane_b32 s13, v201, 13
	v_readlane_b32 s14, v201, 14
	v_readlane_b32 s15, v201, 15
	v_readlane_b32 s16, v201, 16
	v_readlane_b32 s17, v201, 17
	v_readlane_b32 s18, v201, 18
	v_readlane_b32 s19, v201, 19
	v_readlane_b32 s20, v201, 20
	v_readlane_b32 s21, v201, 21
	v_readlane_b32 s22, v201, 22
	v_readlane_b32 s23, v201, 23
	v_readlane_b32 s24, v201, 24
	v_readlane_b32 s25, v201, 25
	v_readlane_b32 s26, v201, 26
	v_readlane_b32 s27, v201, 27
	v_readlane_b32 s28, v201, 28
	v_readlane_b32 s29, v201, 29
	v_readlane_b32 s30, v201, 30
	v_readlane_b32 s31, v201, 31
	v_readlane_b32 s32, v201, 32
	v_readlane_b32 s33, v201, 33
	v_readlane_b32 s34, v201, 34
	v_readlane_b32 s35, v201, 35
	v_readlane_b32 s36, v201, 36
	v_readlane_b32 s37, v201, 37
	v_readlane_b32 s38, v201, 38
	v_readlane_b32 s39, v201, 39
	v_readlane_b32 s40, v201, 40
	v_readlane_b32 s41, v201, 41
	v_readlane_b32 s42, v201, 42
	v_readlane_b32 s43, v201, 43
	v_readlane_b32 s44, v201, 44
	v_readlane_b32 s45, v201, 45
	v_readlane_b32 s46, v201, 46
	v_readlane_b32 s47, v201, 47
	v_readlane_b32 s48, v201, 48
	v_readlane_b32 s49, v201, 49
	v_readlane_b32 s50, v201, 50
	v_readlane_b32 s51, v201, 51
	v_readlane_b32 s52, v201, 52
	v_readlane_b32 s53, v201, 53
	v_readlane_b32 s54, v201, 54
	v_readlane_b32 s55, v201, 55
	v_readlane_b32 s56, v201, 56
	v_readlane_b32 s57, v201, 57
	v_readlane_b32 s58, v201, 58
	v_readlane_b32 s59, v201, 59
	v_readlane_b32 s60, v201, 60
	v_readlane_b32 s61, v201, 61
	v_readlane_b32 s62, v201, 62
	v_readlane_b32 s63, v201, 63
	v_readlane_b32 s64, v202, 0
	v_readlane_b32 s65, v202, 1
	v_readlane_b32 s66, v202, 2
	v_readlane_b32 s67, v202, 3
	v_readlane_b32 s68, v202, 4
	v_readlane_b32 s69, v202, 5
	v_readlane_b32 s70, v202, 6
	v_readlane_b32 s71, v202, 7
	v_readlane_b32 s72, v202, 8
	v_readlane_b32 s73, v202, 9
	v_readlane_b32 s74, v202, 10
	v_readlane_b32 s75, v202, 11
	v_readlane_b32 s76, v202, 12
	v_readlane_b32 s77, v202, 13
	v_readlane_b32 s78, v202, 14
	v_readlane_b32 s79, v202, 15
	v_readlane_b32 s80, v202, 16
	v_readlane_b32 s81, v202, 17
	v_readlane_b32 s82, v202, 18
	v_readlane_b32 s83, v202, 19
	v_readlane_b32 s84, v202, 20
	v_readlane_b32 s85, v202, 21
	v_readlane_b32 s86, v202, 22
	v_readlane_b32 s87, v202, 23
	v_readlane_b32 s88, v202, 24
	v_readlane_b32 s89, v202, 25
	v_readlane_b32 s90, v202, 26
	v_readlane_b32 s91, v202, 27
	v_readlane_b32 s92, v202, 28
	v_readlane_b32 s93, v202, 29
	v_readlane_b32 s94, v202, 30
	v_readlane_b32 s95, v202, 31
	v_readlane_b32 s96, v202, 32
	v_readlane_b32 s97, v202, 33
	v_readlane_b32 s98, v202, 34
	v_readlane_b32 s99, v202, 35
	s_nop 7
